# attention wave remap: map c = wave>>2, row block j = (wave&3)^(2c) so each SIMD hosts one map-0 wave in the unit epilogue; P0 S5 f64 work moved to workgroups with fewer transpose items
# speedup vs baseline: 1.0045x; 1.0045x over previous
.LBB0_56:
	s_or_b64 exec, exec, s[38:39]
	s_add_i32 s0, s72, 0x80
	s_and_b32 s0, s0, 0xff
	v_lshl_add_u32 v6, s0, 9, v1
	s_mov_b32 s0, 0x8000
	v_cmp_gt_i32_e32 vcc, s0, v6
	s_and_saveexec_b64 s[6:7], vcc
	s_cbranch_execz .LBB0_88
	s_waitcnt lgkmcnt(0)
	s_lshl_b32 s8, s28, 9
	s_add_u32 s38, s50, 0x1600000
	s_addc_u32 s39, s51, 0
	s_add_u32 s42, s50, 0x1608000
	v_and_b32_e32 v8, 15, v1
	s_addc_u32 s43, s51, 0
	v_mov_b32_e32 v11, 0
	v_lshlrev_b32_e32 v10, 1, v8
	s_mov_b32 s56, 0xa556c734
	s_add_u32 s44, s50, 0x1640000
	v_lshl_add_u64 v[2:3], s[50:51], 0, v[10:11]
	s_mov_b64 s[4:5], 0x1610000
	s_mov_b32 s57, 0x3ec71de3
	s_mov_b32 s70, 0xb7789f5c
	s_mov_b32 s72, 0x1a01a01a
	v_mov_b32_e32 v19, 0x3f2a01a0
	v_mov_b32_e32 v22, 0x16c16c17
	s_mov_b32 s74, 0x11111111
	s_mov_b32 s76, 0x55555555
	v_mov_b32_e32 v27, 0x3fc55555
	s_mov_b32 s78, 0x54442d18
	s_mov_b32 s82, 0x13a86d09
	v_mov_b32_e32 v33, 0xbf2a01a0
	v_mov_b32_e32 v37, 0xbfc55555
	s_mov_b32 s84, 0xa8c07c9d
	v_mov_b32_e32 v45, 0xbf56c16c
	s_mov_b32 s86, 0xeb1c432d
	s_addc_u32 s45, s51, 0
	v_cmp_eq_u32_e64 s[0:1], 0, v8
	v_lshl_add_u64 v[12:13], v[2:3], 0, s[4:5]
	s_mov_b64 s[54:55], 0
	s_mov_b32 s71, 0x3e927e4f
	v_mov_b64_e32 v[14:15], s[56:57]
	s_mov_b32 s73, 0x3efa01a0
	v_mov_b32_e32 v16, 0x1a01a01a
	v_mov_b32_e32 v20, 0x1a01a01a
	v_mov_b32_e32 v21, v19
	v_mov_b32_e32 v23, 0x3f56c16c
	s_mov_b32 s75, 0x3f811111
	s_mov_b32 s77, 0x3fa55555
	v_mov_b32_e32 v24, 0x55555555
	v_mov_b32_e32 v28, 0x55555555
	v_mov_b32_e32 v29, v27
	s_mov_b32 s79, 0x3ff921fb
	s_mov_b32 s81, 0xbff921fb
	v_mov_b32_e32 v30, 0x67f544e4
	v_mov_b32_e32 v31, 0xbe5ae645
	s_mov_b32 s83, 0x3de61246
	v_mov_b32_e32 v34, 0x1a01a01a
	v_mov_b32_e32 v35, v33
	v_mov_b32_e32 v38, 0x55555555
	v_mov_b32_e32 v39, v37
	v_mov_b32_e32 v40, 0xeff8d898
	v_mov_b32_e32 v41, 0x3e21eed8
	s_mov_b32 s85, 0xbda93974
	v_mov_b32_e32 v42, 0xb7789f5c
	v_mov_b32_e32 v43, 0xbe927e4f
	v_mov_b32_e32 v46, v22
	v_mov_b32_e32 v47, v45
	s_mov_b32 s87, 0xbf1a36e2
	s_movk_i32 s9, 0x7fff
	v_mov_b32_e32 v7, 0xbf1a36e2
	v_mov_b32_e32 v9, 0xeb1c432d
	v_mov_b32_e32 v48, 0xa556c734
	v_mov_b32_e32 v49, 0x3ec71de3
	v_mov_b32_e32 v17, 0x3efa01a0
	v_mov_b32_e32 v50, 0x11111111
	v_mov_b32_e32 v51, 0x3f811111
	v_mov_b32_e32 v25, 0x3fa55555
	v_mov_b32_e32 v68, v6
	s_branch .LBB0_61

.LBB0_563:
	s_andn2_b64 vcc, exec, s[12:13]
	s_cbranch_vccnz .Lmy_pf_skip
	v_mov_b32_e32 v240, 0x22830
	ds_read_b32 v240, v240
	s_waitcnt lgkmcnt(0)
	v_readfirstlane_b32 s98, v240
	s_nop 3
	s_cmp_gt_u32 s98, 0x7ff
	s_cbranch_scc1 .Lmy_pf_skip
	s_and_b32 s4, s98, 0xffffff80
	s_sub_i32 s4, 0x780, s4
	s_lshl_b32 s5, s98, 8
	s_and_b32 s5, s5, 0x7800
	s_add_i32 s4, s4, s5
	s_and_b32 s5, s98, 7
	s_lshl_b32 s5, s5, 8
	v_and_b32_e32 v240, 0xff, v1
	v_lshrrev_b32_e32 v241, 1, v240
	v_add_u32_e32 v241, s4, v241
	v_and_b32_e32 v240, 1, v240
	v_lshlrev_b32_e32 v240, 7, v240
	v_lshlrev_b32_e32 v241, 11, v241
	v_add3_u32 v240, v241, v240, s5
	v_mov_b32_e32 v241, 0
	v_lshl_add_u64 v[242:243], s[38:39], 0, v[240:241]
	global_load_dword v250, v[242:243], off
	v_mov_b32_e32 v243, s64
	v_add_co_u32_e32 v242, vcc, s63, v240
	s_nop 1
	v_addc_co_u32_e32 v243, vcc, 0, v243, vcc
	global_load_dword v250, v[242:243], off
	v_mov_b32_e32 v245, s70
	v_add_co_u32_e32 v244, vcc, s65, v240
	s_nop 1
	v_addc_co_u32_e32 v245, vcc, 0, v245, vcc
	global_load_dword v250, v[244:245], off
